# as previous + explicit vmcnt wait for the dt prefetch before wave 0's scan (the old epilogue waits had covered it)
# baseline (speedup 1.0000x reference)
; __device__ __forceinline__ float ex2(float x) { return __builtin_amdgcn_exp2f(x); }
; #define LAS __attribute__((address_space(3)))
; __device__ __forceinline__ s16x4 trr(LAS unsigned char* p) { return __builtin_bit_cast(s16x4, __builtin_amdgcn_ds_read_tr16_b64_v4i16((LAS v4i16_t*)p)); }
; __device__ __forceinline__ bf16x8 cat8(s16x4 lo, s16x4 hi) { return (bf16x8){lo[0], lo[1], lo[2], lo[3], hi[0], hi[1], hi[2], hi[3]}; }
; #define MFMA32(a, b, c) __builtin_amdgcn_mfma_f32_32x32x16_bf16((a), (b), (c), 0, 0, 0)
; __device__ __forceinline__ void ssd_stream(const Frame& F, const Args& A, int sidx) {
;     ...
;         {
;             const float eL = ex2(arr[127]);
; #pragma unroll
;             for (int i = 0; i < 16; ++i) st[i] *= eL;
; #pragma unroll
;             for (int kg = 0; kg < 2; ++kg) {
;                 s16x4 alo[4], ahi[4], blo[4], bhi[4];
; #pragma unroll
;                 for (int k4 = 0; k4 < 4; ++k4) { const int ks = 4 * kg + k4;
;                     LAS unsigned char* ba = BT + (16 * ks + 8 * hh + qq) * BS_ + (32 * nt + 16 * cb16 + 4 * pp) * 2;
;                     LAS unsigned char* xa = XST + (16 * ks + 8 * hh + qq) * XS_ + (32 * pt + 16 * cb16 + 4 * pp) * 2;
;                     alo[k4] = trr(ba); ahi[k4] = trr(ba + 4 * BS_); blo[k4] = trr(xa); bhi[k4] = trr(xa + 4 * XS_); }
;                 __builtin_amdgcn_sched_barrier(0);
; #pragma unroll
;                 for (int k4 = 0; k4 < 4; ++k4) st = MFMA32(cat8(alo[k4], ahi[k4]), cat8(blo[k4], bhi[k4]), st);
;             }
;         }
;         if (ck < 63) SSD_SCAN((LAS float*)(F.lds + L_ARR + ((ck + 1) & 1) * 1536));
.LBB0_1314:
	s_or_b64 exec, exec, s[26:27]
	v_mov_b32_e32 v19, s78
	ds_read_b32 v19, v19 offset:508
	s_waitcnt lgkmcnt(0)
	v_exp_f32_e32 v20, v19
	v_add_u32_e32 v19, v209, v211
	v_pk_mul_f32 v[16:17], v[16:17], v[20:21] op_sel_hi:[1,0]
	v_pk_mul_f32 v[14:15], v[14:15], v[20:21] op_sel_hi:[1,0]
	v_pk_mul_f32 v[12:13], v[12:13], v[20:21] op_sel_hi:[1,0]
	v_pk_mul_f32 v[10:11], v[10:11], v[20:21] op_sel_hi:[1,0]
	v_pk_mul_f32 v[8:9], v[8:9], v[20:21] op_sel_hi:[1,0]
	v_pk_mul_f32 v[6:7], v[6:7], v[20:21] op_sel_hi:[1,0]
	v_pk_mul_f32 v[4:5], v[4:5], v[20:21] op_sel_hi:[1,0]
	v_pk_mul_f32 v[2:3], v[2:3], v[20:21] op_sel_hi:[1,0]
	ds_read_b64_tr_b16 v[20:21], v19 offset:36864
	ds_read_b64_tr_b16 v[22:23], v19 offset:37952
	ds_read_b64_tr_b16 v[24:25], v227 offset:18432
	ds_read_b64_tr_b16 v[26:27], v227 offset:19008
	ds_read_b64_tr_b16 v[28:29], v19 offset:41216
	ds_read_b64_tr_b16 v[30:31], v19 offset:42304
	ds_read_b64_tr_b16 v[32:33], v227 offset:20736
	ds_read_b64_tr_b16 v[34:35], v227 offset:21312
	ds_read_b64_tr_b16 v[36:37], v19 offset:45568
	ds_read_b64_tr_b16 v[38:39], v19 offset:46656
	ds_read_b64_tr_b16 v[40:41], v227 offset:23040
	ds_read_b64_tr_b16 v[42:43], v227 offset:23616
	ds_read_b64_tr_b16 v[44:45], v19 offset:49920
	ds_read_b64_tr_b16 v[46:47], v19 offset:51008
	ds_read_b64_tr_b16 v[98:99], v227 offset:25344
	ds_read_b64_tr_b16 v[100:101], v227 offset:25920
	s_waitcnt lgkmcnt(12)
	v_mfma_f32_32x32x16_bf16 v[2:17], v[20:23], v[24:27], v[2:17]
	s_waitcnt lgkmcnt(8)
	v_mfma_f32_32x32x16_bf16 v[2:17], v[28:31], v[32:35], v[2:17]
	s_waitcnt lgkmcnt(4)
	v_mfma_f32_32x32x16_bf16 v[2:17], v[36:39], v[40:43], v[2:17]
	s_waitcnt lgkmcnt(0)
	v_mfma_f32_32x32x16_bf16 v[2:17], v[44:47], v[98:101], v[2:17]
	ds_read_b64_tr_b16 v[20:21], v19 offset:54272
	ds_read_b64_tr_b16 v[22:23], v19 offset:55360
	ds_read_b64_tr_b16 v[24:25], v227 offset:27648
	ds_read_b64_tr_b16 v[26:27], v227 offset:28224
	ds_read_b64_tr_b16 v[28:29], v19 offset:58624
	ds_read_b64_tr_b16 v[30:31], v19 offset:59712
	ds_read_b64_tr_b16 v[32:33], v227 offset:29952
	ds_read_b64_tr_b16 v[34:35], v227 offset:30528
	ds_read_b64_tr_b16 v[36:37], v19 offset:62976
	ds_read_b64_tr_b16 v[38:39], v19 offset:64064
	ds_read_b64_tr_b16 v[40:41], v227 offset:32256
	ds_read_b64_tr_b16 v[42:43], v227 offset:32832
	ds_read_b64_tr_b16 v[44:45], v228 offset:62976
	ds_read_b64_tr_b16 v[46:47], v228 offset:64064
	ds_read_b64_tr_b16 v[98:99], v227 offset:34560
	ds_read_b64_tr_b16 v[100:101], v227 offset:35136
	s_waitcnt lgkmcnt(12)
	v_mfma_f32_32x32x16_bf16 v[2:17], v[20:23], v[24:27], v[2:17]
	s_and_b64 s[26:27], s[96:97], s[60:61]
	s_andn2_b64 vcc, exec, s[26:27]
	s_waitcnt lgkmcnt(8)
	v_mfma_f32_32x32x16_bf16 v[2:17], v[28:31], v[32:35], v[2:17]
	s_waitcnt lgkmcnt(4)
	v_mfma_f32_32x32x16_bf16 v[2:17], v[36:39], v[40:43], v[2:17]
	s_waitcnt lgkmcnt(0)
	v_mfma_f32_32x32x16_bf16 v[2:17], v[44:47], v[98:101], v[2:17]
	s_cbranch_vccnz .LBB0_1292
	s_waitcnt vmcnt(2)
	v_pk_mul_f32 v[20:21], v[148:149], v[146:147]
	v_add_u32_e32 v22, -2, v202
	v_add_f32_e32 v19, v21, v20
	v_add_u32_e32 v20, -1, v202
	v_cmp_lt_i32_e32 vcc, v20, v18
	s_andn2_b32 s26, 1, s5
	s_mulk_i32 s26, 0x600
	v_cndmask_b32_e32 v20, v20, v202, vcc
	v_lshlrev_b32_e32 v20, 2, v20
	ds_bpermute_b32 v20, v20, v19
	v_cmp_lt_i32_e32 vcc, v22, v18
	s_waitcnt lgkmcnt(0)
	v_add_f32_e32 v20, v19, v20
	v_cndmask_b32_e64 v19, v20, v19, s[14:15]
	v_cndmask_b32_e32 v20, v22, v202, vcc
	v_lshlrev_b32_e32 v20, 2, v20
	ds_bpermute_b32 v20, v20, v19
	v_add_u32_e32 v22, -4, v202
	v_cmp_lt_i32_e32 vcc, v22, v18
	s_waitcnt lgkmcnt(0)
	v_add_f32_e32 v20, v19, v20
	v_cndmask_b32_e64 v19, v20, v19, s[16:17]
	v_cndmask_b32_e32 v20, v22, v202, vcc
	v_lshlrev_b32_e32 v20, 2, v20
	ds_bpermute_b32 v20, v20, v19
	v_add_u32_e32 v22, -8, v202
	v_cmp_lt_i32_e32 vcc, v22, v18
	s_waitcnt lgkmcnt(0)
	v_add_f32_e32 v20, v19, v20
	v_cndmask_b32_e64 v19, v20, v19, s[18:19]
	v_cndmask_b32_e32 v20, v22, v202, vcc
	v_lshlrev_b32_e32 v20, 2, v20
	ds_bpermute_b32 v20, v20, v19
	v_add_u32_e32 v22, -16, v202
	v_cmp_lt_i32_e32 vcc, v22, v18
	s_waitcnt lgkmcnt(0)
	v_add_f32_e32 v20, v19, v20
	v_cndmask_b32_e64 v19, v20, v19, s[20:21]
	v_cndmask_b32_e32 v20, v22, v202, vcc
	v_lshlrev_b32_e32 v20, 2, v20
	ds_bpermute_b32 v20, v20, v19
	v_subrev_u32_e32 v22, 32, v202
	v_cmp_lt_i32_e32 vcc, v22, v18
	v_add_lshl_u32 v18, v18, v203, 2
	s_waitcnt lgkmcnt(0)
	v_add_f32_e32 v20, v19, v20
	v_cndmask_b32_e64 v19, v20, v19, s[22:23]
	v_cndmask_b32_e32 v20, v22, v202, vcc
	v_lshlrev_b32_e32 v20, 2, v20
	ds_bpermute_b32 v20, v20, v19
	s_waitcnt lgkmcnt(0)
	v_add_f32_e32 v20, v19, v20
	v_cndmask_b32_e64 v19, v20, v19, s[24:25]
	ds_bpermute_b32 v20, v18, v19
	v_sub_f32_e32 v18, v19, v21
	s_waitcnt lgkmcnt(0)
	v_sub_f32_e32 v21, v20, v18
	v_sub_f32_e32 v22, v20, v19
	v_exp_f32_e32 v20, v21
	v_exp_f32_e32 v21, v22
	v_add_u32_e32 v22, s26, v220
	ds_write2st64_b64 v22, v[18:19], v[146:147] offset1:1
	v_pk_mul_f32 v[18:19], v[146:147], v[20:21]
	ds_write_b64 v22, v[18:19] offset:1024
	s_branch .LBB0_1292
